# sample attention stream loads without nt hint (the 4 tokens of a batch share dilation-1 rows in L2)
# speedup vs baseline: 1.0137x; 1.0098x over previous
; __device__ __forceinline__ float fexp2(float x) { return __builtin_amdgcn_exp2f(x); }
; __device__ __forceinline__ void attn_sample_item(const P& p, int wi, int lane) {
;     ...
;         for (int jj = 0; jj < 33; ++jj) {
;             const int j = 4 * jj + kg; const bool valid = j <= 128; const int jc = valid ? j : 128;
;             const int idx = 2048 + i - d * jc;
;             f32x4 k0, k1, v0, v1;
;             if (idx < 2048) { const size_t off = (((size_t)bs * 2048 + idx) * 8 + h) * 128 + 8 * li;
;                 k0 = __builtin_nontemporal_load((const f32x4*)(p.cache_k + off)); k1 = __builtin_nontemporal_load((const f32x4*)(p.cache_k + off + 4)); v0 = __builtin_nontemporal_load((const f32x4*)(p.cache_v + off)); v1 = __builtin_nontemporal_load((const f32x4*)(p.cache_v + off + 4)); }
;             else { const int nr = bs * 4 + (idx - 2048); const float rsn = rstd1[TP + nr]; const int c0 = 4096 + h * 128 + 8 * li;
;                 k0 = acc1_4(ACC1, nr, c0) * rsn; k1 = acc1_4(ACC1, nr, c0 + 4) * rsn; v0 = acc1_4(ACC1, nr, c0 + 1024) * rsn; v1 = acc1_4(ACC1, nr, c0 + 1028) * rsn; }
;             float dot = (q[0] * k0[0] + q[1] * k0[1]) + (q[2] * k0[2] + q[3] * k0[3]) + (q[4] * k1[0] + q[5] * k1[1]) + (q[6] * k1[2] + q[7] * k1[3]);
;             dot += __shfl_xor(dot, 1); dot += __shfl_xor(dot, 2); dot += __shfl_xor(dot, 4); dot += __shfl_xor(dot, 8);
;             const float s = valid ? dot - sl * (float)(d * j) : -INFINITY;
;             const float mn = fmaxf(m, s), sc = fexp2(m - mn), pe = fexp2(s - mn);
;             l = l * sc + pe;
;             acc[0] = acc[0] * sc + pe * v0[0]; acc[1] = acc[1] * sc + pe * v0[1]; acc[2] = acc[2] * sc + pe * v0[2]; acc[3] = acc[3] * sc + pe * v0[3];
;             acc[4] = acc[4] * sc + pe * v1[0]; acc[5] = acc[5] * sc + pe * v1[1]; acc[6] = acc[6] * sc + pe * v1[2]; acc[7] = acc[7] * sc + pe * v1[3];
;             m = mn;
;         }
.Las_sw4:
	s_waitcnt vmcnt(28)
	v_fma_f32 v197, v160, v0, v194
	v_fmac_f32_e32 v197, v161, v1
	v_fmac_f32_e32 v197, v162, v2
	v_fmac_f32_e32 v197, v163, v3
	v_fmac_f32_e32 v197, v164, v4
	v_fmac_f32_e32 v197, v165, v5
	v_fmac_f32_e32 v197, v166, v6
	v_fmac_f32_e32 v197, v167, v7
	s_nop 1
	v_add_f32_dpp v197, v197, v197 row_ror:8 row_mask:0xf bank_mask:0xf
	s_nop 1
	v_add_f32_dpp v197, v197, v197 row_ror:4 row_mask:0xf bank_mask:0xf
	s_nop 1
	v_add_f32_dpp v197, v197, v197 row_ror:2 row_mask:0xf bank_mask:0xf
	s_nop 1
	v_add_f32_dpp v197, v197, v197 row_ror:1 row_mask:0xf bank_mask:0xf
	v_max_f32_e32 v198, v192, v197
	v_sub_f32_e32 v199, v192, v198
	v_sub_f32_e32 v200, v197, v198
	v_exp_f32_e32 v199, v199
	v_exp_f32_e32 v200, v200
	v_mov_b32_e32 v192, v198
	v_fma_f32 v193, v193, v199, v200
	v_mul_f32_e32 v168, v168, v199
	v_mul_f32_e32 v169, v169, v199
	v_mul_f32_e32 v170, v170, v199
	v_mul_f32_e32 v171, v171, v199
	v_mul_f32_e32 v172, v172, v199
	v_mul_f32_e32 v173, v173, v199
	v_mul_f32_e32 v174, v174, v199
	v_mul_f32_e32 v175, v175, v199
	v_fmac_f32_e32 v168, v200, v8
	v_fmac_f32_e32 v169, v200, v9
	v_fmac_f32_e32 v170, v200, v10
	v_fmac_f32_e32 v171, v200, v11
	v_fmac_f32_e32 v172, v200, v12
	v_fmac_f32_e32 v173, v200, v13
	v_fmac_f32_e32 v174, v200, v14
	v_fmac_f32_e32 v175, v200, v15
	v_add_f32_e32 v194, v194, v196
	v_add_u32_e32 v195, s42, v195
	global_load_dwordx4 v[0:3], v195, s[20:21]
	global_load_dwordx4 v[4:7], v195, s[20:21] offset:16
	global_load_dwordx4 v[8:11], v195, s[24:25]
	global_load_dwordx4 v[12:15], v195, s[24:25] offset:16
.Las_slot1:
	s_waitcnt vmcnt(28)
	v_fma_f32 v197, v160, v16, v194
	v_fmac_f32_e32 v197, v161, v17
	v_fmac_f32_e32 v197, v162, v18
	v_fmac_f32_e32 v197, v163, v19
	v_fmac_f32_e32 v197, v164, v20
	v_fmac_f32_e32 v197, v165, v21
	v_fmac_f32_e32 v197, v166, v22
	v_fmac_f32_e32 v197, v167, v23
	s_nop 1
	v_add_f32_dpp v197, v197, v197 row_ror:8 row_mask:0xf bank_mask:0xf
	s_nop 1
	v_add_f32_dpp v197, v197, v197 row_ror:4 row_mask:0xf bank_mask:0xf
	s_nop 1
	v_add_f32_dpp v197, v197, v197 row_ror:2 row_mask:0xf bank_mask:0xf
	s_nop 1
	v_add_f32_dpp v197, v197, v197 row_ror:1 row_mask:0xf bank_mask:0xf
	v_max_f32_e32 v198, v192, v197
	v_sub_f32_e32 v199, v192, v198
	v_sub_f32_e32 v200, v197, v198
	v_exp_f32_e32 v199, v199
	v_exp_f32_e32 v200, v200
	v_mov_b32_e32 v192, v198
	v_fma_f32 v193, v193, v199, v200
	v_mul_f32_e32 v168, v168, v199
	v_mul_f32_e32 v169, v169, v199
	v_mul_f32_e32 v170, v170, v199
	v_mul_f32_e32 v171, v171, v199
	v_mul_f32_e32 v172, v172, v199
	v_mul_f32_e32 v173, v173, v199
	v_mul_f32_e32 v174, v174, v199
	v_mul_f32_e32 v175, v175, v199
	v_fmac_f32_e32 v168, v200, v24
	v_fmac_f32_e32 v169, v200, v25
	v_fmac_f32_e32 v170, v200, v26
	v_fmac_f32_e32 v171, v200, v27
	v_fmac_f32_e32 v172, v200, v28
	v_fmac_f32_e32 v173, v200, v29
	v_fmac_f32_e32 v174, v200, v30
	v_fmac_f32_e32 v175, v200, v31
	v_add_f32_e32 v194, v194, v196
	v_add_u32_e32 v195, s42, v195
	global_load_dwordx4 v[16:19], v195, s[20:21]
	global_load_dwordx4 v[20:23], v195, s[20:21] offset:16
	global_load_dwordx4 v[24:27], v195, s[24:25]
	global_load_dwordx4 v[28:31], v195, s[24:25] offset:16
	s_waitcnt vmcnt(28)
	v_fma_f32 v197, v160, v32, v194
	v_fmac_f32_e32 v197, v161, v33
	v_fmac_f32_e32 v197, v162, v34
	v_fmac_f32_e32 v197, v163, v35
	v_fmac_f32_e32 v197, v164, v36
	v_fmac_f32_e32 v197, v165, v37
	v_fmac_f32_e32 v197, v166, v38
	v_fmac_f32_e32 v197, v167, v39
	s_nop 1
	v_add_f32_dpp v197, v197, v197 row_ror:8 row_mask:0xf bank_mask:0xf
	s_nop 1
	v_add_f32_dpp v197, v197, v197 row_ror:4 row_mask:0xf bank_mask:0xf
	s_nop 1
	v_add_f32_dpp v197, v197, v197 row_ror:2 row_mask:0xf bank_mask:0xf
	s_nop 1
	v_add_f32_dpp v197, v197, v197 row_ror:1 row_mask:0xf bank_mask:0xf
	v_max_f32_e32 v198, v192, v197
	v_sub_f32_e32 v199, v192, v198
	v_sub_f32_e32 v200, v197, v198
	v_exp_f32_e32 v199, v199
	v_exp_f32_e32 v200, v200
	v_mov_b32_e32 v192, v198
	v_fma_f32 v193, v193, v199, v200
	v_mul_f32_e32 v168, v168, v199
	v_mul_f32_e32 v169, v169, v199
	v_mul_f32_e32 v170, v170, v199
	v_mul_f32_e32 v171, v171, v199
	v_mul_f32_e32 v172, v172, v199
	v_mul_f32_e32 v173, v173, v199
	v_mul_f32_e32 v174, v174, v199
	v_mul_f32_e32 v175, v175, v199
	v_fmac_f32_e32 v168, v200, v40
	v_fmac_f32_e32 v169, v200, v41
	v_fmac_f32_e32 v170, v200, v42
	v_fmac_f32_e32 v171, v200, v43
	v_fmac_f32_e32 v172, v200, v44
	v_fmac_f32_e32 v173, v200, v45
	v_fmac_f32_e32 v174, v200, v46
	v_fmac_f32_e32 v175, v200, v47
	v_add_f32_e32 v194, v194, v196
	v_add_u32_e32 v195, s42, v195
	global_load_dwordx4 v[32:35], v195, s[20:21]
	global_load_dwordx4 v[36:39], v195, s[20:21] offset:16
	global_load_dwordx4 v[40:43], v195, s[24:25]
	global_load_dwordx4 v[44:47], v195, s[24:25] offset:16
	s_waitcnt vmcnt(28)
	v_fma_f32 v197, v160, v48, v194
	v_fmac_f32_e32 v197, v161, v49
	v_fmac_f32_e32 v197, v162, v50
	v_fmac_f32_e32 v197, v163, v51
	v_fmac_f32_e32 v197, v164, v52
	v_fmac_f32_e32 v197, v165, v53
	v_fmac_f32_e32 v197, v166, v54
	v_fmac_f32_e32 v197, v167, v55
	s_nop 1
	v_add_f32_dpp v197, v197, v197 row_ror:8 row_mask:0xf bank_mask:0xf
	s_nop 1
	v_add_f32_dpp v197, v197, v197 row_ror:4 row_mask:0xf bank_mask:0xf
	s_nop 1
	v_add_f32_dpp v197, v197, v197 row_ror:2 row_mask:0xf bank_mask:0xf
	s_nop 1
	v_add_f32_dpp v197, v197, v197 row_ror:1 row_mask:0xf bank_mask:0xf
	v_max_f32_e32 v198, v192, v197
	v_sub_f32_e32 v199, v192, v198
	v_sub_f32_e32 v200, v197, v198
	v_exp_f32_e32 v199, v199
	v_exp_f32_e32 v200, v200
	v_mov_b32_e32 v192, v198
	v_fma_f32 v193, v193, v199, v200
	v_mul_f32_e32 v168, v168, v199
	v_mul_f32_e32 v169, v169, v199
	v_mul_f32_e32 v170, v170, v199
	v_mul_f32_e32 v171, v171, v199
	v_mul_f32_e32 v172, v172, v199
	v_mul_f32_e32 v173, v173, v199
	v_mul_f32_e32 v174, v174, v199
	v_mul_f32_e32 v175, v175, v199
	v_fmac_f32_e32 v168, v200, v56
	v_fmac_f32_e32 v169, v200, v57
	v_fmac_f32_e32 v170, v200, v58
	v_fmac_f32_e32 v171, v200, v59
	v_fmac_f32_e32 v172, v200, v60
	v_fmac_f32_e32 v173, v200, v61
	v_fmac_f32_e32 v174, v200, v62
	v_fmac_f32_e32 v175, v200, v63
	v_add_f32_e32 v194, v194, v196
	v_add_u32_e32 v195, s42, v195
	global_load_dwordx4 v[48:51], v195, s[20:21]
	global_load_dwordx4 v[52:55], v195, s[20:21] offset:16
	global_load_dwordx4 v[56:59], v195, s[24:25]
	global_load_dwordx4 v[60:63], v195, s[24:25] offset:16
	s_waitcnt vmcnt(28)
; __device__ __forceinline__ float fexp2(float x) { return __builtin_amdgcn_exp2f(x); }
; __device__ __forceinline__ void attn_sample_item(const P& p, int wi, int lane) {
;     ...
;         for (int jj = 0; jj < 33; ++jj) {
;             const int j = 4 * jj + kg; const bool valid = j <= 128; const int jc = valid ? j : 128;
;             const int idx = 2048 + i - d * jc;
;             f32x4 k0, k1, v0, v1;
;             if (idx < 2048) { const size_t off = (((size_t)bs * 2048 + idx) * 8 + h) * 128 + 8 * li;
;                 k0 = __builtin_nontemporal_load((const f32x4*)(p.cache_k + off)); k1 = __builtin_nontemporal_load((const f32x4*)(p.cache_k + off + 4)); v0 = __builtin_nontemporal_load((const f32x4*)(p.cache_v + off)); v1 = __builtin_nontemporal_load((const f32x4*)(p.cache_v + off + 4)); }
;             else { const int nr = bs * 4 + (idx - 2048); const float rsn = rstd1[TP + nr]; const int c0 = 4096 + h * 128 + 8 * li;
;                 k0 = acc1_4(ACC1, nr, c0) * rsn; k1 = acc1_4(ACC1, nr, c0 + 4) * rsn; v0 = acc1_4(ACC1, nr, c0 + 1024) * rsn; v1 = acc1_4(ACC1, nr, c0 + 1028) * rsn; }
;             float dot = (q[0] * k0[0] + q[1] * k0[1]) + (q[2] * k0[2] + q[3] * k0[3]) + (q[4] * k1[0] + q[5] * k1[1]) + (q[6] * k1[2] + q[7] * k1[3]);
;             dot += __shfl_xor(dot, 1); dot += __shfl_xor(dot, 2); dot += __shfl_xor(dot, 4); dot += __shfl_xor(dot, 8);
;             const float s = valid ? dot - sl * (float)(d * j) : -INFINITY;
;             const float mn = fmaxf(m, s), sc = fexp2(m - mn), pe = fexp2(s - mn);
;             l = l * sc + pe;
;             acc[0] = acc[0] * sc + pe * v0[0]; acc[1] = acc[1] * sc + pe * v0[1]; acc[2] = acc[2] * sc + pe * v0[2]; acc[3] = acc[3] * sc + pe * v0[3];
;             acc[4] = acc[4] * sc + pe * v1[0]; acc[5] = acc[5] * sc + pe * v1[1]; acc[6] = acc[6] * sc + pe * v1[2]; acc[7] = acc[7] * sc + pe * v1[3];
;             m = mn;
;         }
	v_fma_f32 v197, v160, v64, v194
	v_fmac_f32_e32 v197, v161, v65
	v_fmac_f32_e32 v197, v162, v66
	v_fmac_f32_e32 v197, v163, v67
	v_fmac_f32_e32 v197, v164, v68
	v_fmac_f32_e32 v197, v165, v69
	v_fmac_f32_e32 v197, v166, v70
	v_fmac_f32_e32 v197, v167, v71
	s_nop 1
	v_add_f32_dpp v197, v197, v197 row_ror:8 row_mask:0xf bank_mask:0xf
	s_nop 1
	v_add_f32_dpp v197, v197, v197 row_ror:4 row_mask:0xf bank_mask:0xf
	s_nop 1
	v_add_f32_dpp v197, v197, v197 row_ror:2 row_mask:0xf bank_mask:0xf
	s_nop 1
	v_add_f32_dpp v197, v197, v197 row_ror:1 row_mask:0xf bank_mask:0xf
	v_max_f32_e32 v198, v192, v197
	v_sub_f32_e32 v199, v192, v198
	v_sub_f32_e32 v200, v197, v198
	v_exp_f32_e32 v199, v199
	v_exp_f32_e32 v200, v200
	v_mov_b32_e32 v192, v198
	v_fma_f32 v193, v193, v199, v200
	v_mul_f32_e32 v168, v168, v199
	v_mul_f32_e32 v169, v169, v199
	v_mul_f32_e32 v170, v170, v199
	v_mul_f32_e32 v171, v171, v199
	v_mul_f32_e32 v172, v172, v199
	v_mul_f32_e32 v173, v173, v199
	v_mul_f32_e32 v174, v174, v199
	v_mul_f32_e32 v175, v175, v199
	v_fmac_f32_e32 v168, v200, v72
	v_fmac_f32_e32 v169, v200, v73
	v_fmac_f32_e32 v170, v200, v74
	v_fmac_f32_e32 v171, v200, v75
	v_fmac_f32_e32 v172, v200, v76
	v_fmac_f32_e32 v173, v200, v77
	v_fmac_f32_e32 v174, v200, v78
	v_fmac_f32_e32 v175, v200, v79
	v_add_f32_e32 v194, v194, v196
	v_add_u32_e32 v195, s42, v195
	global_load_dwordx4 v[64:67], v195, s[20:21]
	global_load_dwordx4 v[68:71], v195, s[20:21] offset:16
	global_load_dwordx4 v[72:75], v195, s[24:25]
	global_load_dwordx4 v[76:79], v195, s[24:25] offset:16
	s_waitcnt vmcnt(28)
	v_fma_f32 v197, v160, v80, v194
	v_fmac_f32_e32 v197, v161, v81
	v_fmac_f32_e32 v197, v162, v82
	v_fmac_f32_e32 v197, v163, v83
	v_fmac_f32_e32 v197, v164, v84
	v_fmac_f32_e32 v197, v165, v85
	v_fmac_f32_e32 v197, v166, v86
	v_fmac_f32_e32 v197, v167, v87
	s_nop 1
	v_add_f32_dpp v197, v197, v197 row_ror:8 row_mask:0xf bank_mask:0xf
	s_nop 1
	v_add_f32_dpp v197, v197, v197 row_ror:4 row_mask:0xf bank_mask:0xf
	s_nop 1
	v_add_f32_dpp v197, v197, v197 row_ror:2 row_mask:0xf bank_mask:0xf
	s_nop 1
	v_add_f32_dpp v197, v197, v197 row_ror:1 row_mask:0xf bank_mask:0xf
	v_max_f32_e32 v198, v192, v197
	v_sub_f32_e32 v199, v192, v198
	v_sub_f32_e32 v200, v197, v198
	v_exp_f32_e32 v199, v199
	v_exp_f32_e32 v200, v200
	v_mov_b32_e32 v192, v198
	v_fma_f32 v193, v193, v199, v200
	v_mul_f32_e32 v168, v168, v199
	v_mul_f32_e32 v169, v169, v199
	v_mul_f32_e32 v170, v170, v199
	v_mul_f32_e32 v171, v171, v199
	v_mul_f32_e32 v172, v172, v199
	v_mul_f32_e32 v173, v173, v199
	v_mul_f32_e32 v174, v174, v199
	v_mul_f32_e32 v175, v175, v199
	v_fmac_f32_e32 v168, v200, v88
	v_fmac_f32_e32 v169, v200, v89
	v_fmac_f32_e32 v170, v200, v90
	v_fmac_f32_e32 v171, v200, v91
	v_fmac_f32_e32 v172, v200, v92
	v_fmac_f32_e32 v173, v200, v93
	v_fmac_f32_e32 v174, v200, v94
	v_fmac_f32_e32 v175, v200, v95
	v_add_f32_e32 v194, v194, v196
	v_add_u32_e32 v195, s42, v195
	global_load_dwordx4 v[80:83], v195, s[20:21]
	global_load_dwordx4 v[84:87], v195, s[20:21] offset:16
	global_load_dwordx4 v[88:91], v195, s[24:25]
	global_load_dwordx4 v[92:95], v195, s[24:25] offset:16
	s_waitcnt vmcnt(28)
	v_fma_f32 v197, v160, v96, v194
	v_fmac_f32_e32 v197, v161, v97
	v_fmac_f32_e32 v197, v162, v98
	v_fmac_f32_e32 v197, v163, v99
	v_fmac_f32_e32 v197, v164, v100
	v_fmac_f32_e32 v197, v165, v101
	v_fmac_f32_e32 v197, v166, v102
	v_fmac_f32_e32 v197, v167, v103
	s_nop 1
	v_add_f32_dpp v197, v197, v197 row_ror:8 row_mask:0xf bank_mask:0xf
	s_nop 1
	v_add_f32_dpp v197, v197, v197 row_ror:4 row_mask:0xf bank_mask:0xf
	s_nop 1
	v_add_f32_dpp v197, v197, v197 row_ror:2 row_mask:0xf bank_mask:0xf
	s_nop 1
	v_add_f32_dpp v197, v197, v197 row_ror:1 row_mask:0xf bank_mask:0xf
	v_max_f32_e32 v198, v192, v197
	v_sub_f32_e32 v199, v192, v198
	v_sub_f32_e32 v200, v197, v198
	v_exp_f32_e32 v199, v199
	v_exp_f32_e32 v200, v200
	v_mov_b32_e32 v192, v198
	v_fma_f32 v193, v193, v199, v200
	v_mul_f32_e32 v168, v168, v199
	v_mul_f32_e32 v169, v169, v199
	v_mul_f32_e32 v170, v170, v199
	v_mul_f32_e32 v171, v171, v199
	v_mul_f32_e32 v172, v172, v199
	v_mul_f32_e32 v173, v173, v199
	v_mul_f32_e32 v174, v174, v199
	v_mul_f32_e32 v175, v175, v199
	v_fmac_f32_e32 v168, v200, v104
	v_fmac_f32_e32 v169, v200, v105
	v_fmac_f32_e32 v170, v200, v106
	v_fmac_f32_e32 v171, v200, v107
	v_fmac_f32_e32 v172, v200, v108
	v_fmac_f32_e32 v173, v200, v109
	v_fmac_f32_e32 v174, v200, v110
	v_fmac_f32_e32 v175, v200, v111
	v_add_f32_e32 v194, v194, v196
	v_add_u32_e32 v195, s42, v195
	global_load_dwordx4 v[96:99], v195, s[20:21]
	global_load_dwordx4 v[100:103], v195, s[20:21] offset:16
	global_load_dwordx4 v[104:107], v195, s[24:25]
	global_load_dwordx4 v[108:111], v195, s[24:25] offset:16
	s_waitcnt vmcnt(28)
	v_fma_f32 v197, v160, v112, v194
	v_fmac_f32_e32 v197, v161, v113
	v_fmac_f32_e32 v197, v162, v114
	v_fmac_f32_e32 v197, v163, v115
	v_fmac_f32_e32 v197, v164, v116
	v_fmac_f32_e32 v197, v165, v117
	v_fmac_f32_e32 v197, v166, v118
	v_fmac_f32_e32 v197, v167, v119
	s_nop 1
	v_add_f32_dpp v197, v197, v197 row_ror:8 row_mask:0xf bank_mask:0xf
	s_nop 1
	v_add_f32_dpp v197, v197, v197 row_ror:4 row_mask:0xf bank_mask:0xf
	s_nop 1
	v_add_f32_dpp v197, v197, v197 row_ror:2 row_mask:0xf bank_mask:0xf
	s_nop 1
	v_add_f32_dpp v197, v197, v197 row_ror:1 row_mask:0xf bank_mask:0xf
	v_max_f32_e32 v198, v192, v197
	v_sub_f32_e32 v199, v192, v198
	v_sub_f32_e32 v200, v197, v198
	v_exp_f32_e32 v199, v199
	v_exp_f32_e32 v200, v200
	v_mov_b32_e32 v192, v198
	v_fma_f32 v193, v193, v199, v200
	v_mul_f32_e32 v168, v168, v199
	v_mul_f32_e32 v169, v169, v199
	v_mul_f32_e32 v170, v170, v199
	v_mul_f32_e32 v171, v171, v199
	v_mul_f32_e32 v172, v172, v199
	v_mul_f32_e32 v173, v173, v199
	v_mul_f32_e32 v174, v174, v199
	v_mul_f32_e32 v175, v175, v199
	v_fmac_f32_e32 v168, v200, v120
	v_fmac_f32_e32 v169, v200, v121
	v_fmac_f32_e32 v170, v200, v122
	v_fmac_f32_e32 v171, v200, v123
	v_fmac_f32_e32 v172, v200, v124
	v_fmac_f32_e32 v173, v200, v125
	v_fmac_f32_e32 v174, v200, v126
	v_fmac_f32_e32 v175, v200, v127
	v_add_f32_e32 v194, v194, v196
	v_add_u32_e32 v195, s42, v195
	global_load_dwordx4 v[112:115], v195, s[20:21]
	global_load_dwordx4 v[116:119], v195, s[20:21] offset:16
	global_load_dwordx4 v[120:123], v195, s[24:25]
	global_load_dwordx4 v[124:127], v195, s[24:25] offset:16
	s_add_u32 s33, s33, 1
	s_cmp_lt_u32 s33, 11
	s_cbranch_scc1 .Las_trip
; __device__ __forceinline__ float fexp2(float x) { return __builtin_amdgcn_exp2f(x); }
; __device__ __forceinline__ void attn_sample_item(const P& p, int wi, int lane) {
;     ...
;         for (int jj = 0; jj < 33; ++jj) {
;             const int j = 4 * jj + kg; const bool valid = j <= 128; const int jc = valid ? j : 128;
;             const int idx = 2048 + i - d * jc;
;             f32x4 k0, k1, v0, v1;
;             if (idx < 2048) { const size_t off = (((size_t)bs * 2048 + idx) * 8 + h) * 128 + 8 * li;
;                 k0 = __builtin_nontemporal_load((const f32x4*)(p.cache_k + off)); k1 = __builtin_nontemporal_load((const f32x4*)(p.cache_k + off + 4)); v0 = __builtin_nontemporal_load((const f32x4*)(p.cache_v + off)); v1 = __builtin_nontemporal_load((const f32x4*)(p.cache_v + off + 4)); }
;             else { const int nr = bs * 4 + (idx - 2048); const float rsn = rstd1[TP + nr]; const int c0 = 4096 + h * 128 + 8 * li;
;                 k0 = acc1_4(ACC1, nr, c0) * rsn; k1 = acc1_4(ACC1, nr, c0 + 4) * rsn; v0 = acc1_4(ACC1, nr, c0 + 1024) * rsn; v1 = acc1_4(ACC1, nr, c0 + 1028) * rsn; }
;             float dot = (q[0] * k0[0] + q[1] * k0[1]) + (q[2] * k0[2] + q[3] * k0[3]) + (q[4] * k1[0] + q[5] * k1[1]) + (q[6] * k1[2] + q[7] * k1[3]);
;             dot += __shfl_xor(dot, 1); dot += __shfl_xor(dot, 2); dot += __shfl_xor(dot, 4); dot += __shfl_xor(dot, 8);
;             const float s = valid ? dot - sl * (float)(d * j) : -INFINITY;
;             const float mn = fmaxf(m, s), sc = fexp2(m - mn), pe = fexp2(s - mn);
;             l = l * sc + pe;
;             acc[0] = acc[0] * sc + pe * v0[0]; acc[1] = acc[1] * sc + pe * v0[1]; acc[2] = acc[2] * sc + pe * v0[2]; acc[3] = acc[3] * sc + pe * v0[3];
;             acc[4] = acc[4] * sc + pe * v1[0]; acc[5] = acc[5] * sc + pe * v1[1]; acc[6] = acc[6] * sc + pe * v1[2]; acc[7] = acc[7] * sc + pe * v1[3];
;             m = mn;
	s_waitcnt vmcnt(28)
	v_fma_f32 v197, v160, v0, v194
	v_fmac_f32_e32 v197, v161, v1
	v_fmac_f32_e32 v197, v162, v2
	v_fmac_f32_e32 v197, v163, v3
	v_fmac_f32_e32 v197, v164, v4
	v_fmac_f32_e32 v197, v165, v5
	v_fmac_f32_e32 v197, v166, v6
	v_fmac_f32_e32 v197, v167, v7
	s_nop 1
	v_add_f32_dpp v197, v197, v197 row_ror:8 row_mask:0xf bank_mask:0xf
	s_nop 1
	v_add_f32_dpp v197, v197, v197 row_ror:4 row_mask:0xf bank_mask:0xf
	s_nop 1
	v_add_f32_dpp v197, v197, v197 row_ror:2 row_mask:0xf bank_mask:0xf
	s_nop 1
	v_add_f32_dpp v197, v197, v197 row_ror:1 row_mask:0xf bank_mask:0xf
	v_max_f32_e32 v198, v192, v197
	v_sub_f32_e32 v199, v192, v198
	v_sub_f32_e32 v200, v197, v198
	v_exp_f32_e32 v199, v199
	v_exp_f32_e32 v200, v200
	v_mov_b32_e32 v192, v198
	v_fma_f32 v193, v193, v199, v200
	v_mul_f32_e32 v168, v168, v199
	v_mul_f32_e32 v169, v169, v199
	v_mul_f32_e32 v170, v170, v199
	v_mul_f32_e32 v171, v171, v199
	v_mul_f32_e32 v172, v172, v199
	v_mul_f32_e32 v173, v173, v199
	v_mul_f32_e32 v174, v174, v199
	v_mul_f32_e32 v175, v175, v199
	v_fmac_f32_e32 v168, v200, v8
	v_fmac_f32_e32 v169, v200, v9
	v_fmac_f32_e32 v170, v200, v10
	v_fmac_f32_e32 v171, v200, v11
	v_fmac_f32_e32 v172, v200, v12
	v_fmac_f32_e32 v173, v200, v13
	v_fmac_f32_e32 v174, v200, v14
	v_fmac_f32_e32 v175, v200, v15
	v_add_f32_e32 v194, v194, v196
	s_waitcnt vmcnt(24)
	v_fma_f32 v197, v160, v16, v194
	v_fmac_f32_e32 v197, v161, v17
	v_fmac_f32_e32 v197, v162, v18
	v_fmac_f32_e32 v197, v163, v19
	v_fmac_f32_e32 v197, v164, v20
	v_fmac_f32_e32 v197, v165, v21
	v_fmac_f32_e32 v197, v166, v22
	v_fmac_f32_e32 v197, v167, v23
	s_nop 1
	v_add_f32_dpp v197, v197, v197 row_ror:8 row_mask:0xf bank_mask:0xf
	s_nop 1
	v_add_f32_dpp v197, v197, v197 row_ror:4 row_mask:0xf bank_mask:0xf
	s_nop 1
	v_add_f32_dpp v197, v197, v197 row_ror:2 row_mask:0xf bank_mask:0xf
	s_nop 1
	v_add_f32_dpp v197, v197, v197 row_ror:1 row_mask:0xf bank_mask:0xf
	v_max_f32_e32 v198, v192, v197
	v_sub_f32_e32 v199, v192, v198
	v_sub_f32_e32 v200, v197, v198
	v_exp_f32_e32 v199, v199
	v_exp_f32_e32 v200, v200
	v_mov_b32_e32 v192, v198
	v_fma_f32 v193, v193, v199, v200
	v_mul_f32_e32 v168, v168, v199
	v_mul_f32_e32 v169, v169, v199
	v_mul_f32_e32 v170, v170, v199
	v_mul_f32_e32 v171, v171, v199
	v_mul_f32_e32 v172, v172, v199
	v_mul_f32_e32 v173, v173, v199
	v_mul_f32_e32 v174, v174, v199
	v_mul_f32_e32 v175, v175, v199
	v_fmac_f32_e32 v168, v200, v24
	v_fmac_f32_e32 v169, v200, v25
	v_fmac_f32_e32 v170, v200, v26
	v_fmac_f32_e32 v171, v200, v27
	v_fmac_f32_e32 v172, v200, v28
	v_fmac_f32_e32 v173, v200, v29
	v_fmac_f32_e32 v174, v200, v30
	v_fmac_f32_e32 v175, v200, v31
	v_add_f32_e32 v194, v194, v196
	s_waitcnt vmcnt(20)
	v_fma_f32 v197, v160, v32, v194
	v_fmac_f32_e32 v197, v161, v33
	v_fmac_f32_e32 v197, v162, v34
	v_fmac_f32_e32 v197, v163, v35
	v_fmac_f32_e32 v197, v164, v36
	v_fmac_f32_e32 v197, v165, v37
	v_fmac_f32_e32 v197, v166, v38
	v_fmac_f32_e32 v197, v167, v39
	s_nop 1
	v_add_f32_dpp v197, v197, v197 row_ror:8 row_mask:0xf bank_mask:0xf
	s_nop 1
	v_add_f32_dpp v197, v197, v197 row_ror:4 row_mask:0xf bank_mask:0xf
	s_nop 1
	v_add_f32_dpp v197, v197, v197 row_ror:2 row_mask:0xf bank_mask:0xf
	s_nop 1
	v_add_f32_dpp v197, v197, v197 row_ror:1 row_mask:0xf bank_mask:0xf
	v_max_f32_e32 v198, v192, v197
	v_sub_f32_e32 v199, v192, v198
	v_sub_f32_e32 v200, v197, v198
	v_exp_f32_e32 v199, v199
	v_exp_f32_e32 v200, v200
	v_mov_b32_e32 v192, v198
	v_fma_f32 v193, v193, v199, v200
	v_mul_f32_e32 v168, v168, v199
	v_mul_f32_e32 v169, v169, v199
	v_mul_f32_e32 v170, v170, v199
	v_mul_f32_e32 v171, v171, v199
	v_mul_f32_e32 v172, v172, v199
	v_mul_f32_e32 v173, v173, v199
	v_mul_f32_e32 v174, v174, v199
	v_mul_f32_e32 v175, v175, v199
	v_fmac_f32_e32 v168, v200, v40
	v_fmac_f32_e32 v169, v200, v41
	v_fmac_f32_e32 v170, v200, v42
	v_fmac_f32_e32 v171, v200, v43
	v_fmac_f32_e32 v172, v200, v44
	v_fmac_f32_e32 v173, v200, v45
	v_fmac_f32_e32 v174, v200, v46
	v_fmac_f32_e32 v175, v200, v47
	v_add_f32_e32 v194, v194, v196
	s_waitcnt vmcnt(16)
	v_fma_f32 v197, v160, v48, v194
	v_fmac_f32_e32 v197, v161, v49
	v_fmac_f32_e32 v197, v162, v50
	v_fmac_f32_e32 v197, v163, v51
	v_fmac_f32_e32 v197, v164, v52
	v_fmac_f32_e32 v197, v165, v53
	v_fmac_f32_e32 v197, v166, v54
	v_fmac_f32_e32 v197, v167, v55
	s_nop 1
	v_add_f32_dpp v197, v197, v197 row_ror:8 row_mask:0xf bank_mask:0xf
	s_nop 1
	v_add_f32_dpp v197, v197, v197 row_ror:4 row_mask:0xf bank_mask:0xf
	s_nop 1
	v_add_f32_dpp v197, v197, v197 row_ror:2 row_mask:0xf bank_mask:0xf
	s_nop 1
	v_add_f32_dpp v197, v197, v197 row_ror:1 row_mask:0xf bank_mask:0xf
	v_max_f32_e32 v198, v192, v197
	v_sub_f32_e32 v199, v192, v198
	v_sub_f32_e32 v200, v197, v198
	v_exp_f32_e32 v199, v199
	v_exp_f32_e32 v200, v200
	v_mov_b32_e32 v192, v198
	v_fma_f32 v193, v193, v199, v200
	v_mul_f32_e32 v168, v168, v199
	v_mul_f32_e32 v169, v169, v199
	v_mul_f32_e32 v170, v170, v199
	v_mul_f32_e32 v171, v171, v199
	v_mul_f32_e32 v172, v172, v199
	v_mul_f32_e32 v173, v173, v199
	v_mul_f32_e32 v174, v174, v199
	v_mul_f32_e32 v175, v175, v199
	v_fmac_f32_e32 v168, v200, v56
	v_fmac_f32_e32 v169, v200, v57
	v_fmac_f32_e32 v170, v200, v58
	v_fmac_f32_e32 v171, v200, v59
	v_fmac_f32_e32 v172, v200, v60
	v_fmac_f32_e32 v173, v200, v61
	v_fmac_f32_e32 v174, v200, v62
	v_fmac_f32_e32 v175, v200, v63
	v_add_f32_e32 v194, v194, v196
	s_waitcnt vmcnt(12)
; __device__ __forceinline__ float fexp2(float x) { return __builtin_amdgcn_exp2f(x); }
; __device__ __forceinline__ void attn_sample_item(const P& p, int wi, int lane) {
;     ...
;         for (int jj = 0; jj < 33; ++jj) {
;             const int j = 4 * jj + kg; const bool valid = j <= 128; const int jc = valid ? j : 128;
;             const int idx = 2048 + i - d * jc;
;             f32x4 k0, k1, v0, v1;
;             if (idx < 2048) { const size_t off = (((size_t)bs * 2048 + idx) * 8 + h) * 128 + 8 * li;
;                 k0 = __builtin_nontemporal_load((const f32x4*)(p.cache_k + off)); k1 = __builtin_nontemporal_load((const f32x4*)(p.cache_k + off + 4)); v0 = __builtin_nontemporal_load((const f32x4*)(p.cache_v + off)); v1 = __builtin_nontemporal_load((const f32x4*)(p.cache_v + off + 4)); }
;             else { const int nr = bs * 4 + (idx - 2048); const float rsn = rstd1[TP + nr]; const int c0 = 4096 + h * 128 + 8 * li;
;                 k0 = acc1_4(ACC1, nr, c0) * rsn; k1 = acc1_4(ACC1, nr, c0 + 4) * rsn; v0 = acc1_4(ACC1, nr, c0 + 1024) * rsn; v1 = acc1_4(ACC1, nr, c0 + 1028) * rsn; }
;             float dot = (q[0] * k0[0] + q[1] * k0[1]) + (q[2] * k0[2] + q[3] * k0[3]) + (q[4] * k1[0] + q[5] * k1[1]) + (q[6] * k1[2] + q[7] * k1[3]);
;             dot += __shfl_xor(dot, 1); dot += __shfl_xor(dot, 2); dot += __shfl_xor(dot, 4); dot += __shfl_xor(dot, 8);
;             const float s = valid ? dot - sl * (float)(d * j) : -INFINITY;
;             const float mn = fmaxf(m, s), sc = fexp2(m - mn), pe = fexp2(s - mn);
;             l = l * sc + pe;
;             acc[0] = acc[0] * sc + pe * v0[0]; acc[1] = acc[1] * sc + pe * v0[1]; acc[2] = acc[2] * sc + pe * v0[2]; acc[3] = acc[3] * sc + pe * v0[3];
;             acc[4] = acc[4] * sc + pe * v1[0]; acc[5] = acc[5] * sc + pe * v1[1]; acc[6] = acc[6] * sc + pe * v1[2]; acc[7] = acc[7] * sc + pe * v1[3];
;             m = mn;
	v_fma_f32 v197, v160, v64, v194
	v_fmac_f32_e32 v197, v161, v65
	v_fmac_f32_e32 v197, v162, v66
	v_fmac_f32_e32 v197, v163, v67
	v_fmac_f32_e32 v197, v164, v68
	v_fmac_f32_e32 v197, v165, v69
	v_fmac_f32_e32 v197, v166, v70
	v_fmac_f32_e32 v197, v167, v71
	s_nop 1
	v_add_f32_dpp v197, v197, v197 row_ror:8 row_mask:0xf bank_mask:0xf
	s_nop 1
	v_add_f32_dpp v197, v197, v197 row_ror:4 row_mask:0xf bank_mask:0xf
	s_nop 1
	v_add_f32_dpp v197, v197, v197 row_ror:2 row_mask:0xf bank_mask:0xf
	s_nop 1
	v_add_f32_dpp v197, v197, v197 row_ror:1 row_mask:0xf bank_mask:0xf
	v_max_f32_e32 v198, v192, v197
	v_sub_f32_e32 v199, v192, v198
	v_sub_f32_e32 v200, v197, v198
	v_exp_f32_e32 v199, v199
	v_exp_f32_e32 v200, v200
	v_mov_b32_e32 v192, v198
	v_fma_f32 v193, v193, v199, v200
	v_mul_f32_e32 v168, v168, v199
	v_mul_f32_e32 v169, v169, v199
	v_mul_f32_e32 v170, v170, v199
	v_mul_f32_e32 v171, v171, v199
	v_mul_f32_e32 v172, v172, v199
	v_mul_f32_e32 v173, v173, v199
	v_mul_f32_e32 v174, v174, v199
	v_mul_f32_e32 v175, v175, v199
	v_fmac_f32_e32 v168, v200, v72
	v_fmac_f32_e32 v169, v200, v73
	v_fmac_f32_e32 v170, v200, v74
	v_fmac_f32_e32 v171, v200, v75
	v_fmac_f32_e32 v172, v200, v76
	v_fmac_f32_e32 v173, v200, v77
	v_fmac_f32_e32 v174, v200, v78
	v_fmac_f32_e32 v175, v200, v79
	v_add_f32_e32 v194, v194, v196
	s_waitcnt vmcnt(8)
	v_fma_f32 v197, v160, v80, v194
	v_fmac_f32_e32 v197, v161, v81
	v_fmac_f32_e32 v197, v162, v82
	v_fmac_f32_e32 v197, v163, v83
	v_fmac_f32_e32 v197, v164, v84
	v_fmac_f32_e32 v197, v165, v85
	v_fmac_f32_e32 v197, v166, v86
	v_fmac_f32_e32 v197, v167, v87
	s_nop 1
	v_add_f32_dpp v197, v197, v197 row_ror:8 row_mask:0xf bank_mask:0xf
	s_nop 1
	v_add_f32_dpp v197, v197, v197 row_ror:4 row_mask:0xf bank_mask:0xf
	s_nop 1
	v_add_f32_dpp v197, v197, v197 row_ror:2 row_mask:0xf bank_mask:0xf
	s_nop 1
	v_add_f32_dpp v197, v197, v197 row_ror:1 row_mask:0xf bank_mask:0xf
	v_max_f32_e32 v198, v192, v197
	v_sub_f32_e32 v199, v192, v198
	v_sub_f32_e32 v200, v197, v198
	v_exp_f32_e32 v199, v199
	v_exp_f32_e32 v200, v200
	v_mov_b32_e32 v192, v198
	v_fma_f32 v193, v193, v199, v200
	v_mul_f32_e32 v168, v168, v199
	v_mul_f32_e32 v169, v169, v199
	v_mul_f32_e32 v170, v170, v199
	v_mul_f32_e32 v171, v171, v199
	v_mul_f32_e32 v172, v172, v199
	v_mul_f32_e32 v173, v173, v199
	v_mul_f32_e32 v174, v174, v199
	v_mul_f32_e32 v175, v175, v199
	v_fmac_f32_e32 v168, v200, v88
	v_fmac_f32_e32 v169, v200, v89
	v_fmac_f32_e32 v170, v200, v90
	v_fmac_f32_e32 v171, v200, v91
	v_fmac_f32_e32 v172, v200, v92
	v_fmac_f32_e32 v173, v200, v93
	v_fmac_f32_e32 v174, v200, v94
	v_fmac_f32_e32 v175, v200, v95
	v_add_f32_e32 v194, v194, v196
	s_waitcnt vmcnt(4)
	v_fma_f32 v197, v160, v96, v194
	v_fmac_f32_e32 v197, v161, v97
	v_fmac_f32_e32 v197, v162, v98
	v_fmac_f32_e32 v197, v163, v99
	v_fmac_f32_e32 v197, v164, v100
	v_fmac_f32_e32 v197, v165, v101
	v_fmac_f32_e32 v197, v166, v102
	v_fmac_f32_e32 v197, v167, v103
	s_nop 1
	v_add_f32_dpp v197, v197, v197 row_ror:8 row_mask:0xf bank_mask:0xf
	s_nop 1
	v_add_f32_dpp v197, v197, v197 row_ror:4 row_mask:0xf bank_mask:0xf
	s_nop 1
	v_add_f32_dpp v197, v197, v197 row_ror:2 row_mask:0xf bank_mask:0xf
	s_nop 1
	v_add_f32_dpp v197, v197, v197 row_ror:1 row_mask:0xf bank_mask:0xf
	v_max_f32_e32 v198, v192, v197
	v_sub_f32_e32 v199, v192, v198
	v_sub_f32_e32 v200, v197, v198
	v_exp_f32_e32 v199, v199
	v_exp_f32_e32 v200, v200
	v_mov_b32_e32 v192, v198
	v_fma_f32 v193, v193, v199, v200
	v_mul_f32_e32 v168, v168, v199
	v_mul_f32_e32 v169, v169, v199
	v_mul_f32_e32 v170, v170, v199
	v_mul_f32_e32 v171, v171, v199
	v_mul_f32_e32 v172, v172, v199
	v_mul_f32_e32 v173, v173, v199
	v_mul_f32_e32 v174, v174, v199
	v_mul_f32_e32 v175, v175, v199
	v_fmac_f32_e32 v168, v200, v104
	v_fmac_f32_e32 v169, v200, v105
	v_fmac_f32_e32 v170, v200, v106
	v_fmac_f32_e32 v171, v200, v107
	v_fmac_f32_e32 v172, v200, v108
	v_fmac_f32_e32 v173, v200, v109
	v_fmac_f32_e32 v174, v200, v110
	v_fmac_f32_e32 v175, v200, v111
	v_add_f32_e32 v194, v194, v196
	s_waitcnt vmcnt(0)
; __device__ __forceinline__ float fexp2(float x) { return __builtin_amdgcn_exp2f(x); }
; __device__ __forceinline__ void attn_sample_item(const P& p, int wi, int lane) {
;     ...
;     float mt = fmaxf(m, __shfl_xor(m, 16)); mt = fmaxf(mt, __shfl_xor(mt, 32));
;     const float f = fexp2(m - mt);
;     l *= f; l += __shfl_xor(l, 16); l += __shfl_xor(l, 32);
;     const float inv = 1.f / l;
;     float* o = (float*)(ws + O_ATTS) + (size_t)srow * 1024 + h * 128 + 8 * li;
; #pragma unroll
;     for (int e = 0; e < 8; ++e) { float a = acc[e] * f; a += __shfl_xor(a, 16); a += __shfl_xor(a, 32); acc[e] = a * inv; }
;     if (kg == 0) { *(f32x4*)o = (f32x4){acc[0], acc[1], acc[2], acc[3]}; *(f32x4*)(o + 4) = (f32x4){acc[4], acc[5], acc[6], acc[7]}; }
; __global__ void __launch_bounds__(NTHR) fwd_megakernel(P p) {
;     ...
;           if (w < 4) { for (int wi = w * G + blockIdx.x; wi < 1024; wi += G * 4) attn_sample_item(p, wi, t0 & 63); }
	v_fma_f32 v197, v160, v112, v194
	v_fmac_f32_e32 v197, v161, v113
	v_fmac_f32_e32 v197, v162, v114
	v_fmac_f32_e32 v197, v163, v115
	v_fmac_f32_e32 v197, v164, v116
	v_fmac_f32_e32 v197, v165, v117
	v_fmac_f32_e32 v197, v166, v118
	v_fmac_f32_e32 v197, v167, v119
	s_nop 1
	v_add_f32_dpp v197, v197, v197 row_ror:8 row_mask:0xf bank_mask:0xf
	s_nop 1
	v_add_f32_dpp v197, v197, v197 row_ror:4 row_mask:0xf bank_mask:0xf
	s_nop 1
	v_add_f32_dpp v197, v197, v197 row_ror:2 row_mask:0xf bank_mask:0xf
	s_nop 1
	v_add_f32_dpp v197, v197, v197 row_ror:1 row_mask:0xf bank_mask:0xf
	v_max_f32_e32 v198, v192, v197
	v_sub_f32_e32 v199, v192, v198
	v_sub_f32_e32 v200, v197, v198
	v_exp_f32_e32 v199, v199
	v_exp_f32_e32 v200, v200
	v_mov_b32_e32 v192, v198
	v_fma_f32 v193, v193, v199, v200
	v_mul_f32_e32 v168, v168, v199
	v_mul_f32_e32 v169, v169, v199
	v_mul_f32_e32 v170, v170, v199
	v_mul_f32_e32 v171, v171, v199
	v_mul_f32_e32 v172, v172, v199
	v_mul_f32_e32 v173, v173, v199
	v_mul_f32_e32 v174, v174, v199
	v_mul_f32_e32 v175, v175, v199
	v_fmac_f32_e32 v168, v200, v120
	v_fmac_f32_e32 v169, v200, v121
	v_fmac_f32_e32 v170, v200, v122
	v_fmac_f32_e32 v171, v200, v123
	v_fmac_f32_e32 v172, v200, v124
	v_fmac_f32_e32 v173, v200, v125
	v_fmac_f32_e32 v174, v200, v126
	v_fmac_f32_e32 v175, v200, v127
	v_and_b32_e32 v182, 63, v230
	v_xor_b32_e32 v183, 16, v182
	v_lshlrev_b32_e32 v183, 2, v183
	v_xor_b32_e32 v182, 32, v182
	v_lshlrev_b32_e32 v182, 2, v182
	ds_bpermute_b32 v197, v183, v192
	s_waitcnt lgkmcnt(0)
	v_max_f32_e32 v198, v192, v197
	ds_bpermute_b32 v197, v182, v198
	s_waitcnt lgkmcnt(0)
	v_max_f32_e32 v198, v198, v197
	v_sub_f32_e32 v199, v192, v198
	v_exp_f32_e32 v199, v199
	s_nop 0
	v_mul_f32_e32 v193, v193, v199
	v_mul_f32_e32 v168, v168, v199
	v_mul_f32_e32 v169, v169, v199
	v_mul_f32_e32 v170, v170, v199
	v_mul_f32_e32 v171, v171, v199
	v_mul_f32_e32 v172, v172, v199
	v_mul_f32_e32 v173, v173, v199
	v_mul_f32_e32 v174, v174, v199
	v_mul_f32_e32 v175, v175, v199
	ds_bpermute_b32 v0, v183, v193
	ds_bpermute_b32 v1, v183, v168
	ds_bpermute_b32 v2, v183, v169
	ds_bpermute_b32 v3, v183, v170
	ds_bpermute_b32 v4, v183, v171
	ds_bpermute_b32 v5, v183, v172
	ds_bpermute_b32 v6, v183, v173
	ds_bpermute_b32 v7, v183, v174
	ds_bpermute_b32 v8, v183, v175
	s_waitcnt lgkmcnt(0)
	v_add_f32_e32 v193, v193, v0
	v_add_f32_e32 v168, v168, v1
	v_add_f32_e32 v169, v169, v2
	v_add_f32_e32 v170, v170, v3
	v_add_f32_e32 v171, v171, v4
	v_add_f32_e32 v172, v172, v5
	v_add_f32_e32 v173, v173, v6
	v_add_f32_e32 v174, v174, v7
	v_add_f32_e32 v175, v175, v8
	ds_bpermute_b32 v0, v182, v193
	ds_bpermute_b32 v1, v182, v168
	ds_bpermute_b32 v2, v182, v169
	ds_bpermute_b32 v3, v182, v170
	ds_bpermute_b32 v4, v182, v171
	ds_bpermute_b32 v5, v182, v172
	ds_bpermute_b32 v6, v182, v173
	ds_bpermute_b32 v7, v182, v174
	ds_bpermute_b32 v8, v182, v175
	s_waitcnt lgkmcnt(0)
	v_add_f32_e32 v193, v193, v0
	v_add_f32_e32 v168, v168, v1
	v_add_f32_e32 v169, v169, v2
	v_add_f32_e32 v170, v170, v3
	v_add_f32_e32 v171, v171, v4
	v_add_f32_e32 v172, v172, v5
	v_add_f32_e32 v173, v173, v6
	v_add_f32_e32 v174, v174, v7
	v_add_f32_e32 v175, v175, v8
	v_rcp_f32_e32 v197, v193
	s_nop 0
	v_fma_f32 v198, -v193, v197, 1.0
	v_fma_f32 v197, v198, v197, v197
	v_mul_f32_e32 v168, v168, v197
	v_mul_f32_e32 v169, v169, v197
	v_mul_f32_e32 v170, v170, v197
	v_mul_f32_e32 v171, v171, v197
	v_mul_f32_e32 v172, v172, v197
	v_mul_f32_e32 v173, v173, v197
	v_mul_f32_e32 v174, v174, v197
	v_mul_f32_e32 v175, v175, v197
	v_and_b32_e32 v182, 15, v230
	v_lshlrev_b32_e32 v182, 5, v182
	s_lshl_b32 s43, s17, 12
	s_add_u32 s43, s43, s23
	v_add_u32_e32 v182, s43, v182
	s_mov_b64 exec, 0xffff
	global_store_dwordx4 v182, v[168:171], s[30:31]
	global_store_dwordx4 v182, v[172:175], s[30:31] offset:16
	s_mov_b64 exec, -1
	s_add_i32 s3, s3, s77
	s_cmpk_gt_i32 s3, 0x3ff
	s_cbranch_scc0 .Las_item
